# MV1: attention loop: the last P.V MFMA group (4 MFMAs) moved across the X section's closing barrier to the head of the following softmax section (matrix pipe idle there while the partner's X waits on
# speedup vs baseline: 1.0074x; 1.0032x over previous
.Lmy_attn_top:
	s_waitcnt lgkmcnt(0)
	s_barrier
	v_mfma_f32_32x32x16_bf16 v[20:35], v[148:151], v[204:207], v[20:35]
	v_mfma_f32_32x32x16_bf16 v[20:35], v[152:155], v[216:219], v[20:35]
	v_mfma_f32_32x32x16_bf16 v[20:35], v[156:159], v[220:223], v[20:35]
	v_mfma_f32_32x32x16_bf16 v[20:35], v[160:163], v[224:227], v[20:35]
	v_fma_f32 v183, v183, v184, v185

.LBB0_633:
	s_waitcnt lgkmcnt(0)
	s_barrier
	v_lshl_add_u32 v187, s53, 14, v173
	ds_read_b64_tr_b16 v[188:189], v187 offset:0
	ds_read_b64_tr_b16 v[190:191], v187 offset:0x800
	ds_read_b64_tr_b16 v[192:193], v187 offset:0x1000
	ds_read_b64_tr_b16 v[194:195], v187 offset:0x1800
	ds_read_b64_tr_b16 v[196:197], v187 offset:0x2000
	ds_read_b64_tr_b16 v[198:199], v187 offset:0x2800
	ds_read_b64_tr_b16 v[200:201], v187 offset:0x3000
	ds_read_b64_tr_b16 v[202:203], v187 offset:0x3800
	s_lshl_b32 s52, s49, 14
	v_add_u32_e32 v208, s52, v174
	ds_read_b128 v[68:71], v208 offset:0
	ds_read_b128 v[72:75], v208 offset:0x2000
	v_add_u32_e32 v209, s52, v175
	ds_read_b128 v[204:207], v209 offset:0
	ds_read_b128 v[216:219], v209 offset:0x2000
	v_add_u32_e32 v210, s52, v176
	ds_read_b128 v[220:223], v210 offset:0
	ds_read_b128 v[224:227], v210 offset:0x2000
	v_add_u32_e32 v211, s52, v177
	ds_read_b128 v[228:231], v211 offset:0
	ds_read_b128 v[232:235], v211 offset:0x2000
	s_waitcnt lgkmcnt(4)
	v_mfma_f32_32x32x16_bf16 v[84:99], v[68:71], v[128:131], 0
	v_mfma_f32_32x32x16_bf16 v[68:83], v[72:75], v[128:131], 0
	v_mfma_f32_32x32x16_bf16 v[84:99], v[204:207], v[124:127], v[84:99]
	v_mfma_f32_32x32x16_bf16 v[68:83], v[216:219], v[124:127], v[68:83]
	ds_read_b128 v[204:207], v208 offset:0x80
	ds_read_b128 v[216:219], v208 offset:0x2080
	ds_read_b128 v[236:239], v209 offset:0x80
	ds_read_b128 v[242:245], v209 offset:0x2080
	s_waitcnt lgkmcnt(4)
	v_mfma_f32_32x32x16_bf16 v[84:99], v[220:223], v[120:123], v[84:99]
	v_mfma_f32_32x32x16_bf16 v[68:83], v[224:227], v[120:123], v[68:83]
	v_mfma_f32_32x32x16_bf16 v[84:99], v[228:231], v[116:119], v[84:99]
	v_mfma_f32_32x32x16_bf16 v[68:83], v[232:235], v[116:119], v[68:83]
	ds_read_b128 v[220:223], v210 offset:0x80
	ds_read_b128 v[224:227], v210 offset:0x2080
	ds_read_b128 v[228:231], v211 offset:0x80
	ds_read_b128 v[232:235], v211 offset:0x2080
	s_waitcnt lgkmcnt(4)
	v_mfma_f32_32x32x16_bf16 v[84:99], v[204:207], v[112:115], v[84:99]
	v_mfma_f32_32x32x16_bf16 v[68:83], v[216:219], v[112:115], v[68:83]
	v_mfma_f32_32x32x16_bf16 v[84:99], v[236:239], v[108:111], v[84:99]
	v_mfma_f32_32x32x16_bf16 v[68:83], v[242:245], v[108:111], v[68:83]
	s_waitcnt lgkmcnt(0)
	v_mfma_f32_32x32x16_bf16 v[84:99], v[220:223], v[104:107], v[84:99]
	v_mfma_f32_32x32x16_bf16 v[68:83], v[224:227], v[104:107], v[68:83]
	v_mfma_f32_32x32x16_bf16 v[84:99], v[228:231], v[100:103], v[84:99]
	v_mfma_f32_32x32x16_bf16 v[68:83], v[232:235], v[100:103], v[68:83]
	ds_read_b64_tr_b16 v[204:205], v187 offset:0x200
	ds_read_b64_tr_b16 v[206:207], v187 offset:0xa00
	ds_read_b64_tr_b16 v[216:217], v187 offset:0x1200
	ds_read_b64_tr_b16 v[218:219], v187 offset:0x1a00
	ds_read_b64_tr_b16 v[220:221], v187 offset:0x2200
	ds_read_b64_tr_b16 v[222:223], v187 offset:0x2a00
	ds_read_b64_tr_b16 v[224:225], v187 offset:0x3200
	ds_read_b64_tr_b16 v[226:227], v187 offset:0x3a00
	s_waitcnt lgkmcnt(8)
	v_mfma_f32_32x32x16_bf16 v[4:19], v[148:151], v[188:191], v[4:19]
	s_lshl_b32 s19, s51, 14
	s_add_i32 s8, s19, 0
	v_add_u32_e32 v236, s8, v179
	s_waitcnt vmcnt(0)
	v_mfma_f32_32x32x16_bf16 v[4:19], v[152:155], v[192:195], v[4:19]
	ds_write_b128 v236, v[144:147]
	v_add_u32_e32 v236, s8, v178
	v_mfma_f32_32x32x16_bf16 v[4:19], v[156:159], v[196:199], v[4:19]
	ds_write_b128 v236, v[136:139]
	v_add_u32_e32 v236, s8, v180
	v_mfma_f32_32x32x16_bf16 v[4:19], v[160:163], v[200:203], v[4:19]
	ds_read_b64_tr_b16 v[188:189], v187 offset:0x400
	ds_read_b64_tr_b16 v[190:191], v187 offset:0xc00
	ds_read_b64_tr_b16 v[192:193], v187 offset:0x1400
	ds_read_b64_tr_b16 v[194:195], v187 offset:0x1c00
	ds_read_b64_tr_b16 v[196:197], v187 offset:0x2400
	ds_read_b64_tr_b16 v[198:199], v187 offset:0x2c00
	ds_read_b64_tr_b16 v[200:201], v187 offset:0x3400
	ds_read_b64_tr_b16 v[202:203], v187 offset:0x3c00
	s_waitcnt lgkmcnt(10)
	v_mfma_f32_32x32x16_bf16 v[52:67], v[148:151], v[204:207], v[52:67]
	ds_write_b128 v236, v[140:143] offset:49152
	v_add_u32_e32 v236, s8, v181
	v_mfma_f32_32x32x16_bf16 v[52:67], v[152:155], v[216:219], v[52:67]
	ds_write_b128 v236, v[132:135] offset:49152
	s_add_i32 s48, s48, 1
	v_mfma_f32_32x32x16_bf16 v[52:67], v[156:159], v[220:223], v[52:67]
	s_sub_i32 s8, s50, s47
	s_min_u32 s36, s50, s8
	s_lshl_b64 s[8:9], s[36:37], 10
	s_cmp_lt_u32 s50, s47
	s_cselect_b32 s16, s30, s20
	s_cselect_b32 s17, s31, s21
	v_mfma_f32_32x32x16_bf16 v[52:67], v[160:163], v[224:227], v[52:67]
	ds_read_b64_tr_b16 v[204:205], v187 offset:0x600
	ds_read_b64_tr_b16 v[206:207], v187 offset:0xe00
	ds_read_b64_tr_b16 v[216:217], v187 offset:0x1600
	ds_read_b64_tr_b16 v[218:219], v187 offset:0x1e00
	ds_read_b64_tr_b16 v[220:221], v187 offset:0x2600
	ds_read_b64_tr_b16 v[222:223], v187 offset:0x2e00
	ds_read_b64_tr_b16 v[224:225], v187 offset:0x3600
	ds_read_b64_tr_b16 v[226:227], v187 offset:0x3e00
	s_waitcnt lgkmcnt(10)
	v_mfma_f32_32x32x16_bf16 v[36:51], v[148:151], v[188:191], v[36:51]
	s_cselect_b32 s36, s42, s26
	s_cselect_b32 s54, s43, s27
	s_add_u32 s16, s16, s8
	s_addc_u32 s17, s17, s9
	s_add_u32 s8, s36, s8
	s_addc_u32 s9, s54, s9
	v_mfma_f32_32x32x16_bf16 v[36:51], v[152:155], v[192:195], v[36:51]
	global_load_dwordx4 v[144:147], v2, s[8:9]
	s_add_u32 s8, s8, 0x8000
	s_addc_u32 s9, s9, 0
	v_mfma_f32_32x32x16_bf16 v[36:51], v[156:159], v[196:199], v[36:51]
	global_load_dwordx4 v[136:139], v2, s[8:9]
	global_load_dwordx4 v[140:143], v2, s[16:17]
	v_mfma_f32_32x32x16_bf16 v[36:51], v[160:163], v[200:203], v[36:51]
	s_add_u32 s16, s16, 0x8000
	s_addc_u32 s17, s17, 0
	global_load_dwordx4 v[132:135], v2, s[16:17]
	s_waitcnt lgkmcnt(0)
